# v27 plus attention end-barrier loop copy: tile counter and DMA pointer stepping moved in front of the iteration-end barrier
# baseline (speedup 1.0000x reference)
; #define BAR() do { asm volatile("s_waitcnt lgkmcnt(0)" ::: "memory"); __builtin_amdgcn_s_barrier(); asm volatile("" ::: "memory"); } while (0)
; #define RESC(a) do { if (__any((a) < 1.f)) { if (hi == 0) al_l[r32] = (a); asm volatile("s_waitcnt lgkmcnt(0)" ::: "memory"); \
;     for (int r = 0; r < 16; ++r) { const float a_ = al_l[crow(r, hi)]; ls[r] *= a_; for (int d = 0; d < 4; ++d) o[d][r] *= a_; } } } while (0)
; __device__ __forceinline__ void body(const unsigned char* Q8b, const unsigned char* K8h, const unsigned char* VT8h, const bf16_t* Gb, bf16_t* Ob, int seq, char* lds, const int wid, ...
;     ...
;   for (int i = 0; i + 2 < NT; i += 2) {
;     ...
;     RESC(alA); BAR();
;     s0 = (s0 + 2) & 3;
.LBB0_373:
	s_add_i32 s45, s45, 2
	s_add_u32 s100, s100, 0x4000
	s_addc_u32 s101, s101, 0
	s_add_u32 s98, s98, 0x8000
	s_addc_u32 s99, s99, 0
	s_cmpk_gt_u32 s45, 0x7d
	s_waitcnt lgkmcnt(0)
	s_barrier
	s_cbranch_scc1 .LBB0_385
	s_branch .Lc2_374
